# attention branch-combine: the 16-lane row-norm butterflies use DPP moves (quad_perm / row_half_mirror / row_mirror) instead of ds_bpermute + lgkmcnt waits, bit-identical (on top of v15)
# baseline (speedup 1.0000x reference)
.LBB0_474:
	s_or_b64 exec, exec, s[8:9]
	v_mov_b32_e32 v215, v1
	v_lshl_add_u64 v[2:3], s[58:59], 0, v[214:215]
	v_lshlrev_b32_e32 v0, 10, v99
	s_waitcnt lgkmcnt(0)
	s_barrier
	v_lshl_add_u64 v[6:7], v[2:3], 0, v[0:1]
	global_load_dwordx4 v[2:5], v[6:7], off
	v_lshlrev_b32_e32 v0, 5, v231
	v_lshlrev_b32_e32 v8, 2, v230
	v_lshl_add_u32 v9, v99, 8, v41
	v_lshl_add_u32 v12, v49, 8, v41
	global_load_dwordx4 v[30:33], v0, s[16:17] offset:16
	global_load_dwordx4 v[34:37], v0, s[16:17]
	v_xor_b32_e32 v48, 4, v8
	v_xor_b32_e32 v47, 8, v8
	v_xor_b32_e32 v46, 16, v8
	v_xor_b32_e32 v45, 32, v8
	ds_read_b128 v[8:11], v9
	ds_read_b128 v[50:53], v12
	v_add_co_u32_e32 v12, vcc, 0x1000, v6
	v_xor_b32_e32 v26, 0x80000000, v212
	s_nop 0
	v_addc_co_u32_e32 v13, vcc, 0, v7, vcc
	global_load_dwordx4 v[54:57], v[12:13], off
	v_add_co_u32_e32 v14, vcc, s86, v6
	v_mov_b32_e32 v27, v26
	s_nop 0
	v_addc_co_u32_e32 v15, vcc, 0, v7, vcc
	v_add_co_u32_e32 v12, vcc, 0x3000, v6
	s_waitcnt lgkmcnt(1)
	v_lshlrev_b32_e32 v28, 16, v8
	v_addc_co_u32_e32 v13, vcc, 0, v7, vcc
	global_load_dwordx4 v[22:25], v[14:15], off
	global_load_dwordx4 v[18:21], v[12:13], off
	v_and_b32_e32 v29, 0xffff0000, v8
	v_lshlrev_b32_e32 v8, 16, v9
	v_and_b32_e32 v9, 0xffff0000, v9
	v_lshlrev_b32_e32 v58, 16, v10
	v_and_b32_e32 v59, 0xffff0000, v10
	v_lshlrev_b32_e32 v10, 16, v11
	v_and_b32_e32 v11, 0xffff0000, v11
	s_waitcnt lgkmcnt(0)
	v_lshlrev_b32_e32 v60, 16, v50
	v_and_b32_e32 v61, 0xffff0000, v50
	v_lshlrev_b32_e32 v50, 16, v51
	v_and_b32_e32 v51, 0xffff0000, v51
	v_add_co_u32_e32 v16, vcc, s87, v6
	s_lshl_b64 s[8:9], s[54:55], 11
	s_nop 0
	v_addc_co_u32_e32 v17, vcc, 0, v7, vcc
	v_add_co_u32_e32 v12, vcc, 0x5000, v6
	s_movk_i32 s10, 0x6000
	s_nop 0
	v_addc_co_u32_e32 v13, vcc, 0, v7, vcc
	s_add_u32 s8, s82, s8
	s_addc_u32 s9, s83, s9
	s_waitcnt vmcnt(5)
	v_lshlrev_b32_e32 v14, 16, v2
	v_and_b32_e32 v15, 0xffff0000, v2
	v_lshlrev_b32_e32 v2, 16, v3
	v_and_b32_e32 v3, 0xffff0000, v3
	v_lshlrev_b32_e32 v62, 16, v4
	v_and_b32_e32 v63, 0xffff0000, v4
	v_lshlrev_b32_e32 v4, 16, v5
	v_and_b32_e32 v5, 0xffff0000, v5
	v_pk_fma_f32 v[64:65], v[212:213], v[14:15], v[28:29] neg_lo:[1,0,0] neg_hi:[1,0,0]
	v_pk_fma_f32 v[66:67], v[26:27], v[2:3], v[8:9]
	v_pk_fma_f32 v[58:59], v[212:213], v[62:63], v[58:59] neg_lo:[1,0,0] neg_hi:[1,0,0]
	v_pk_fma_f32 v[62:63], v[26:27], v[4:5], v[10:11]
	v_pk_mul_f32 v[2:3], v[66:67], v[66:67]
	v_pk_mul_f32 v[4:5], v[64:65], v[64:65]
	v_pk_mul_f32 v[8:9], v[62:63], v[62:63]
	v_pk_mul_f32 v[10:11], v[58:59], v[58:59]
	v_pk_mov_b32 v[14:15], v[4:5], v[2:3] op_sel:[1,0]
	v_mov_b32_e32 v5, v3
	v_mov_b32_e32 v2, v8
	v_mov_b32_e32 v3, v10
	v_mov_b32_e32 v10, v9
	v_pk_add_f32 v[4:5], v[14:15], v[4:5]
	v_pk_add_f32 v[2:3], v[2:3], v[10:11]
	v_add_f32_e32 v0, v4, v5
	v_add_f32_e32 v0, v3, v0
	v_add_f32_e32 v0, v2, v0
	s_nop 1
	v_mov_b32_dpp v3, v0 quad_perm:[1,0,3,2] row_mask:0xf bank_mask:0xf
	s_waitcnt vmcnt(3)
	v_pk_mul_f32 v[28:29], v[34:35], s[52:53] op_sel_hi:[1,0]
	v_pk_mul_f32 v[34:35], v[36:37], s[52:53] op_sel_hi:[1,0]
	s_waitcnt vmcnt(2)
	v_lshlrev_b32_e32 v36, 16, v54
	v_and_b32_e32 v37, 0xffff0000, v54
	s_waitcnt lgkmcnt(0)
	v_add_f32_e32 v0, v0, v3
	s_nop 1
	v_mov_b32_dpp v5, v0 quad_perm:[2,3,0,1] row_mask:0xf bank_mask:0xf
	v_lshlrev_b32_e32 v54, 16, v55
	v_and_b32_e32 v55, 0xffff0000, v55
	v_pk_fma_f32 v[60:61], v[212:213], v[36:37], v[60:61] neg_lo:[1,0,0] neg_hi:[1,0,0]
	v_pk_fma_f32 v[54:55], v[26:27], v[54:55], v[50:51]
	s_waitcnt lgkmcnt(0)
	v_add_f32_e32 v0, v0, v5
	s_nop 1
	v_mov_b32_dpp v68, v0 row_half_mirror row_mask:0xf bank_mask:0xf
	v_lshlrev_b32_e32 v36, 16, v52
	v_and_b32_e32 v37, 0xffff0000, v52
	v_lshlrev_b32_e32 v50, 16, v53
	v_and_b32_e32 v51, 0xffff0000, v53
	s_waitcnt lgkmcnt(0)
	v_add_f32_e32 v0, v0, v68
	s_nop 1
	v_mov_b32_dpp v68, v0 row_mirror row_mask:0xf bank_mask:0xf
	v_lshlrev_b32_e32 v52, 16, v56
	v_and_b32_e32 v53, 0xffff0000, v56
	v_lshlrev_b32_e32 v56, 16, v57
	v_and_b32_e32 v57, 0xffff0000, v57
	s_waitcnt lgkmcnt(0)
	v_add_f32_e32 v0, v0, v68
	v_pk_fma_f32 v[68:69], v[212:213], v[52:53], v[36:37] neg_lo:[1,0,0] neg_hi:[1,0,0]
	v_pk_fma_f32 v[70:71], v[26:27], v[56:57], v[50:51]
	v_pk_mul_f32 v[36:37], v[54:55], v[54:55]
	v_pk_mul_f32 v[50:51], v[60:61], v[60:61]
	v_fmamk_f32 v0, v0, 0x3c000000, v227
	v_pk_mov_b32 v[52:53], v[50:51], v[36:37] op_sel:[1,0]
	v_mov_b32_e32 v51, v37
	v_pk_add_f32 v[36:37], v[52:53], v[50:51]
	v_pk_mul_f32 v[50:51], v[70:71], v[70:71]
	v_pk_mul_f32 v[52:53], v[68:69], v[68:69]
	v_mov_b32_e32 v56, v50
	v_mov_b32_e32 v57, v52
	v_mov_b32_e32 v52, v51
	v_pk_add_f32 v[50:51], v[56:57], v[52:53]
	v_add_f32_e32 v36, v36, v37
	v_add_f32_e32 v36, v51, v36
	v_add_f32_e32 v56, v50, v36
	s_nop 1
	v_mov_b32_dpp v57, v56 quad_perm:[1,0,3,2] row_mask:0xf bank_mask:0xf
	v_rsq_f32_e32 v0, v0
	global_load_dwordx4 v[14:17], v[16:17], off
	s_nop 0
	global_load_dwordx4 v[10:13], v[12:13], off
	v_add_co_u32_e32 v2, vcc, s10, v6
	v_pk_mul_f32 v[50:51], v[64:65], v[0:1] op_sel_hi:[1,0]
	s_waitcnt lgkmcnt(0)
	v_add_f32_e32 v64, v56, v57
	s_nop 1
	v_mov_b32_dpp v65, v64 quad_perm:[2,3,0,1] row_mask:0xf bank_mask:0xf
	v_pk_mul_f32 v[52:53], v[66:67], v[0:1] op_sel_hi:[1,0]
	v_pk_mul_f32 v[56:57], v[58:59], v[0:1] op_sel_hi:[1,0]
	v_pk_mul_f32 v[58:59], v[62:63], v[0:1] op_sel_hi:[1,0]
	v_addc_co_u32_e32 v3, vcc, 0, v7, vcc
	s_waitcnt lgkmcnt(0)
	v_add_f32_e32 v0, v64, v65
	s_nop 1
	v_mov_b32_dpp v62, v0 row_half_mirror row_mask:0xf bank_mask:0xf
	v_pk_mul_f32 v[30:31], v[30:31], s[52:53] op_sel_hi:[1,0]
	v_pk_mul_f32 v[32:33], v[32:33], s[52:53] op_sel_hi:[1,0]
	v_add_co_u32_e32 v4, vcc, 0x7000, v6
	s_waitcnt lgkmcnt(0)
	v_add_f32_e32 v62, v0, v62
	s_nop 1
	v_mov_b32_dpp v63, v62 row_mirror row_mask:0xf bank_mask:0xf
	v_lshl_add_u64 v[36:37], s[8:9], 0, v[214:215]
	v_pk_mul_f32 v[52:53], v[34:35], v[52:53]
	v_pk_mul_f32 v[50:51], v[28:29], v[50:51]
	v_pk_mul_f32 v[58:59], v[32:33], v[58:59]
	v_pk_mul_f32 v[56:57], v[30:31], v[56:57]
	v_lshlrev_b32_e32 v0, 11, v99
	v_addc_co_u32_e32 v5, vcc, 0, v7, vcc
	v_cvt_pk_bf16_f32 v50, v50, v51
	v_cvt_pk_bf16_f32 v51, v52, v53
	v_cvt_pk_bf16_f32 v52, v56, v57
	v_cvt_pk_bf16_f32 v53, v58, v59
	v_lshl_add_u64 v[56:57], v[36:37], 0, v[0:1]
	s_waitcnt lgkmcnt(0)
	v_add_f32_e32 v0, v62, v63
	global_load_dwordx4 v[6:9], v[2:3], off
	s_nop 0
	global_load_dwordx4 v[2:5], v[4:5], off
	v_fmamk_f32 v0, v0, 0x3c000000, v227
	global_store_dwordx4 v[56:57], v[50:53], off
	v_rsq_f32_e32 v0, v0
	s_waitcnt vmcnt(6)
	v_lshlrev_b32_e32 v64, 16, v22
	v_lshl_add_u32 v50, v44, 8, v41
	ds_read_b128 v[50:53], v50
	v_pk_mul_f32 v[58:59], v[60:61], v[0:1] op_sel_hi:[1,0]
	v_pk_mul_f32 v[60:61], v[54:55], v[0:1] op_sel_hi:[1,0]
	v_lshl_add_u32 v54, v43, 8, v41
	ds_read_b128 v[54:57], v54
	s_waitcnt lgkmcnt(1)
	v_lshlrev_b32_e32 v62, 16, v50
	v_and_b32_e32 v63, 0xffff0000, v50
	v_lshlrev_b32_e32 v50, 16, v51
	v_and_b32_e32 v51, 0xffff0000, v51
	v_and_b32_e32 v65, 0xffff0000, v22
	v_lshlrev_b32_e32 v22, 16, v23
	v_and_b32_e32 v23, 0xffff0000, v23
	v_pk_fma_f32 v[62:63], v[212:213], v[64:65], v[62:63] neg_lo:[1,0,0] neg_hi:[1,0,0]
	v_pk_fma_f32 v[50:51], v[26:27], v[22:23], v[50:51]
	v_lshlrev_b32_e32 v22, 16, v52
	v_and_b32_e32 v23, 0xffff0000, v52
	v_lshlrev_b32_e32 v52, 16, v53
	v_and_b32_e32 v53, 0xffff0000, v53
	v_lshlrev_b32_e32 v64, 16, v24
	v_and_b32_e32 v65, 0xffff0000, v24
	v_lshlrev_b32_e32 v24, 16, v25
	v_and_b32_e32 v25, 0xffff0000, v25
	v_pk_fma_f32 v[64:65], v[212:213], v[64:65], v[22:23] neg_lo:[1,0,0] neg_hi:[1,0,0]
	v_pk_fma_f32 v[52:53], v[26:27], v[24:25], v[52:53]
	v_pk_mul_f32 v[22:23], v[50:51], v[50:51]
	v_pk_mul_f32 v[24:25], v[62:63], v[62:63]
	s_nop 0
	v_pk_mov_b32 v[66:67], v[24:25], v[22:23] op_sel:[1,0]
	v_mov_b32_e32 v25, v23
	v_pk_add_f32 v[22:23], v[66:67], v[24:25]
	v_pk_mul_f32 v[24:25], v[52:53], v[52:53]
	v_pk_mul_f32 v[66:67], v[64:65], v[64:65]
	v_mov_b32_e32 v72, v24
	v_mov_b32_e32 v73, v66
	v_mov_b32_e32 v66, v25
	v_pk_add_f32 v[24:25], v[72:73], v[66:67]
	v_add_f32_e32 v22, v22, v23
	v_add_f32_e32 v22, v25, v22
	v_add_f32_e32 v66, v24, v22
	s_nop 1
	v_mov_b32_dpp v67, v66 quad_perm:[1,0,3,2] row_mask:0xf bank_mask:0xf
	v_pk_mul_f32 v[24:25], v[34:35], v[60:61]
	v_pk_mul_f32 v[22:23], v[28:29], v[58:59]
	v_pk_mul_f32 v[58:59], v[68:69], v[0:1] op_sel_hi:[1,0]
	v_pk_mul_f32 v[60:61], v[70:71], v[0:1] op_sel_hi:[1,0]
	s_waitcnt lgkmcnt(0)
	v_add_f32_e32 v0, v66, v67
	s_nop 1
	v_mov_b32_dpp v66, v0 quad_perm:[2,3,0,1] row_mask:0xf bank_mask:0xf
	v_pk_mul_f32 v[60:61], v[32:33], v[60:61]
	v_pk_mul_f32 v[58:59], v[30:31], v[58:59]
	v_cvt_pk_bf16_f32 v22, v22, v23
	v_cvt_pk_bf16_f32 v23, v24, v25
	s_waitcnt lgkmcnt(0)
	v_add_f32_e32 v66, v0, v66
	s_nop 1
	v_mov_b32_dpp v67, v66 row_half_mirror row_mask:0xf bank_mask:0xf
	v_lshlrev_b32_e32 v0, 11, v49
	v_cvt_pk_bf16_f32 v24, v58, v59
	v_cvt_pk_bf16_f32 v25, v60, v61
	v_lshl_add_u64 v[58:59], v[36:37], 0, v[0:1]
	s_waitcnt lgkmcnt(0)
	v_add_f32_e32 v0, v66, v67
	v_lshlrev_b32_e32 v60, 16, v54
	v_and_b32_e32 v61, 0xffff0000, v54
	v_lshlrev_b32_e32 v54, 16, v55
	v_and_b32_e32 v55, 0xffff0000, v55
	s_waitcnt vmcnt(5)
	v_lshlrev_b32_e32 v66, 16, v18
	v_and_b32_e32 v67, 0xffff0000, v18
	v_lshlrev_b32_e32 v18, 16, v19
	v_and_b32_e32 v19, 0xffff0000, v19
	v_pk_fma_f32 v[60:61], v[212:213], v[66:67], v[60:61] neg_lo:[1,0,0] neg_hi:[1,0,0]
	v_pk_fma_f32 v[54:55], v[26:27], v[18:19], v[54:55]
	v_lshlrev_b32_e32 v18, 16, v56
	v_and_b32_e32 v19, 0xffff0000, v56
	v_lshlrev_b32_e32 v56, 16, v57
	v_and_b32_e32 v57, 0xffff0000, v57
	v_lshlrev_b32_e32 v66, 16, v20
	v_and_b32_e32 v67, 0xffff0000, v20
	v_lshlrev_b32_e32 v20, 16, v21
	v_and_b32_e32 v21, 0xffff0000, v21
	v_pk_fma_f32 v[66:67], v[212:213], v[66:67], v[18:19] neg_lo:[1,0,0] neg_hi:[1,0,0]
	v_pk_fma_f32 v[56:57], v[26:27], v[20:21], v[56:57]
	v_pk_mul_f32 v[18:19], v[54:55], v[54:55]
	v_pk_mul_f32 v[20:21], v[60:61], v[60:61]
	s_nop 1
	v_mov_b32_dpp v49, v0 row_mirror row_mask:0xf bank_mask:0xf
	v_pk_mov_b32 v[68:69], v[20:21], v[18:19] op_sel:[1,0]
	v_mov_b32_e32 v21, v19
	v_pk_add_f32 v[18:19], v[68:69], v[20:21]
	v_pk_mul_f32 v[20:21], v[56:57], v[56:57]
	v_pk_mul_f32 v[68:69], v[66:67], v[66:67]
	v_mov_b32_e32 v70, v20
	v_mov_b32_e32 v71, v68
	v_mov_b32_e32 v68, v21
	v_pk_add_f32 v[20:21], v[70:71], v[68:69]
	v_add_f32_e32 v18, v18, v19
	v_add_f32_e32 v18, v21, v18
	v_add_f32_e32 v18, v20, v18
	s_nop 1
	v_mov_b32_dpp v19, v18 quad_perm:[1,0,3,2] row_mask:0xf bank_mask:0xf
	global_store_dwordx4 v[58:59], v[22:25], off
	s_waitcnt lgkmcnt(0)
	v_add_f32_e32 v0, v0, v49
	v_fmamk_f32 v0, v0, 0x3c000000, v227
	v_rsq_f32_e32 v0, v0
	s_waitcnt lgkmcnt(0)
	v_add_f32_e32 v22, v18, v19
	s_nop 1
	v_mov_b32_dpp v23, v22 quad_perm:[2,3,0,1] row_mask:0xf bank_mask:0xf
	v_pk_mul_f32 v[20:21], v[50:51], v[0:1] op_sel_hi:[1,0]
	v_pk_mul_f32 v[18:19], v[62:63], v[0:1] op_sel_hi:[1,0]
	v_pk_mul_f32 v[24:25], v[52:53], v[0:1] op_sel_hi:[1,0]
	s_waitcnt lgkmcnt(0)
	v_add_f32_e32 v49, v22, v23
	s_nop 1
	v_mov_b32_dpp v50, v49 row_half_mirror row_mask:0xf bank_mask:0xf
	v_pk_mul_f32 v[22:23], v[64:65], v[0:1] op_sel_hi:[1,0]
	v_pk_mul_f32 v[20:21], v[34:35], v[20:21]
	v_pk_mul_f32 v[18:19], v[28:29], v[18:19]
	v_pk_mul_f32 v[22:23], v[30:31], v[22:23]
	s_waitcnt lgkmcnt(0)
	v_add_f32_e32 v0, v49, v50
	s_nop 1
	v_mov_b32_dpp v49, v0 row_mirror row_mask:0xf bank_mask:0xf
	v_pk_mul_f32 v[24:25], v[32:33], v[24:25]
	v_cvt_pk_bf16_f32 v18, v18, v19
	v_cvt_pk_bf16_f32 v19, v20, v21
	v_cvt_pk_bf16_f32 v20, v22, v23
	v_lshl_add_u32 v22, v42, 8, v41
	v_cvt_pk_bf16_f32 v21, v24, v25
	ds_read_b128 v[22:25], v22
	s_waitcnt lgkmcnt(1)
	v_add_f32_e32 v0, v0, v49
	v_fmamk_f32 v0, v0, 0x3c000000, v227
	v_rsq_f32_e32 v58, v0
	v_lshl_add_u32 v0, v40, 8, v41
	ds_read_b128 v[50:53], v0
	s_waitcnt lgkmcnt(1)
	v_lshlrev_b32_e32 v62, 16, v22
	v_and_b32_e32 v63, 0xffff0000, v22
	v_lshlrev_b32_e32 v22, 16, v23
	v_and_b32_e32 v23, 0xffff0000, v23
	s_waitcnt vmcnt(5)
	v_lshlrev_b32_e32 v64, 16, v14
	v_and_b32_e32 v65, 0xffff0000, v14
	v_lshlrev_b32_e32 v14, 16, v15
	v_and_b32_e32 v15, 0xffff0000, v15
	v_pk_fma_f32 v[62:63], v[212:213], v[64:65], v[62:63] neg_lo:[1,0,0] neg_hi:[1,0,0]
	v_pk_fma_f32 v[22:23], v[26:27], v[14:15], v[22:23]
	v_lshlrev_b32_e32 v14, 16, v24
	v_and_b32_e32 v15, 0xffff0000, v24
	v_lshlrev_b32_e32 v24, 16, v25
	v_and_b32_e32 v25, 0xffff0000, v25
	v_lshlrev_b32_e32 v64, 16, v16
	v_and_b32_e32 v65, 0xffff0000, v16
	v_lshlrev_b32_e32 v16, 16, v17
	v_and_b32_e32 v17, 0xffff0000, v17
	v_pk_fma_f32 v[64:65], v[212:213], v[64:65], v[14:15] neg_lo:[1,0,0] neg_hi:[1,0,0]
	v_pk_fma_f32 v[24:25], v[26:27], v[16:17], v[24:25]
	v_pk_mul_f32 v[14:15], v[22:23], v[22:23]
	v_pk_mul_f32 v[16:17], v[62:63], v[62:63]
	s_nop 0
	v_pk_mov_b32 v[68:69], v[16:17], v[14:15] op_sel:[1,0]
	v_mov_b32_e32 v17, v15
	v_pk_add_f32 v[14:15], v[68:69], v[16:17]
	v_pk_mul_f32 v[16:17], v[24:25], v[24:25]
	v_pk_mul_f32 v[68:69], v[64:65], v[64:65]
	v_mov_b32_e32 v70, v16
	v_mov_b32_e32 v71, v68
	v_mov_b32_e32 v68, v17
	v_pk_add_f32 v[16:17], v[70:71], v[68:69]
	v_add_f32_e32 v0, v14, v15
	v_add_f32_e32 v0, v17, v0
	v_add_f32_e32 v16, v16, v0
	s_nop 1
	v_mov_b32_dpp v17, v16 quad_perm:[1,0,3,2] row_mask:0xf bank_mask:0xf
	v_lshlrev_b32_e32 v0, 11, v44
	v_lshl_add_u64 v[14:15], v[36:37], 0, v[0:1]
	global_store_dwordx4 v[14:15], v[18:21], off
	v_pk_mul_f32 v[14:15], v[60:61], v[58:59] op_sel_hi:[1,0]
	s_waitcnt lgkmcnt(0)
	v_add_f32_e32 v0, v16, v17
	s_nop 1
	v_mov_b32_dpp v20, v0 quad_perm:[2,3,0,1] row_mask:0xf bank_mask:0xf
	v_pk_mul_f32 v[16:17], v[54:55], v[58:59] op_sel_hi:[1,0]
	v_pk_mul_f32 v[14:15], v[28:29], v[14:15]
	v_pk_mul_f32 v[16:17], v[34:35], v[16:17]
	v_cvt_pk_bf16_f32 v14, v14, v15
	s_waitcnt lgkmcnt(0)
	v_add_f32_e32 v0, v0, v20
	s_nop 1
	v_mov_b32_dpp v44, v0 row_half_mirror row_mask:0xf bank_mask:0xf
	v_pk_mul_f32 v[20:21], v[56:57], v[58:59] op_sel_hi:[1,0]
	v_cvt_pk_bf16_f32 v15, v16, v17
	v_pk_mul_f32 v[20:21], v[32:33], v[20:21]
	s_waitcnt vmcnt(5)
	v_lshlrev_b32_e32 v54, 16, v10
	v_cvt_pk_bf16_f32 v17, v20, v21
	v_lshlrev_b32_e32 v20, 16, v50
	v_and_b32_e32 v21, 0xffff0000, v50
	v_lshlrev_b32_e32 v50, 16, v51
	v_and_b32_e32 v51, 0xffff0000, v51
	v_and_b32_e32 v55, 0xffff0000, v10
	v_lshlrev_b32_e32 v10, 16, v11
	v_and_b32_e32 v11, 0xffff0000, v11
	v_pk_fma_f32 v[20:21], v[212:213], v[54:55], v[20:21] neg_lo:[1,0,0] neg_hi:[1,0,0]
	v_pk_fma_f32 v[50:51], v[26:27], v[10:11], v[50:51]
	v_lshlrev_b32_e32 v10, 16, v52
	v_and_b32_e32 v11, 0xffff0000, v52
	v_lshlrev_b32_e32 v52, 16, v53
	v_and_b32_e32 v53, 0xffff0000, v53
	v_lshlrev_b32_e32 v54, 16, v12
	v_and_b32_e32 v55, 0xffff0000, v12
	v_lshlrev_b32_e32 v12, 16, v13
	v_and_b32_e32 v13, 0xffff0000, v13
	v_pk_fma_f32 v[54:55], v[212:213], v[54:55], v[10:11] neg_lo:[1,0,0] neg_hi:[1,0,0]
	v_pk_fma_f32 v[52:53], v[26:27], v[12:13], v[52:53]
	v_pk_mul_f32 v[10:11], v[50:51], v[50:51]
	v_pk_mul_f32 v[12:13], v[20:21], v[20:21]
	s_waitcnt lgkmcnt(0)
	v_add_f32_e32 v44, v0, v44
	v_pk_mov_b32 v[56:57], v[12:13], v[10:11] op_sel:[1,0]
	v_mov_b32_e32 v13, v11
	s_nop 1
	v_mov_b32_dpp v49, v44 row_mirror row_mask:0xf bank_mask:0xf
	v_pk_add_f32 v[10:11], v[56:57], v[12:13]
	v_pk_mul_f32 v[12:13], v[52:53], v[52:53]
	v_pk_mul_f32 v[56:57], v[54:55], v[54:55]
	v_pk_mul_f32 v[18:19], v[66:67], v[58:59] op_sel_hi:[1,0]
	v_mov_b32_e32 v58, v12
	v_mov_b32_e32 v59, v56
	v_mov_b32_e32 v56, v13
	v_pk_add_f32 v[12:13], v[58:59], v[56:57]
	v_add_f32_e32 v10, v10, v11
	v_pk_mul_f32 v[18:19], v[30:31], v[18:19]
	v_add_f32_e32 v10, v13, v10
	v_cvt_pk_bf16_f32 v16, v18, v19
	v_add_f32_e32 v19, v12, v10
	v_lshlrev_b32_e32 v0, 11, v43
	s_waitcnt lgkmcnt(0)
	v_add_f32_e32 v18, v44, v49
	s_nop 1
	v_mov_b32_dpp v43, v19 quad_perm:[1,0,3,2] row_mask:0xf bank_mask:0xf
	v_fmamk_f32 v18, v18, 0x3c000000, v227
	v_rsq_f32_e32 v18, v18
	v_lshl_add_u64 v[10:11], v[36:37], 0, v[0:1]
	global_store_dwordx4 v[10:11], v[14:17], off
	s_waitcnt lgkmcnt(0)
	v_add_f32_e32 v0, v19, v43
	v_pk_mul_f32 v[10:11], v[62:63], v[18:19] op_sel_hi:[1,0]
	v_pk_mul_f32 v[12:13], v[22:23], v[18:19] op_sel_hi:[1,0]
	s_nop 1
	v_mov_b32_dpp v19, v0 quad_perm:[2,3,0,1] row_mask:0xf bank_mask:0xf
	v_pk_mul_f32 v[12:13], v[34:35], v[12:13]
	v_pk_mul_f32 v[10:11], v[28:29], v[10:11]
	s_waitcnt lgkmcnt(0)
	v_add_f32_e32 v0, v0, v19
	v_pk_mul_f32 v[14:15], v[64:65], v[18:19] op_sel_hi:[1,0]
	v_pk_mul_f32 v[16:17], v[24:25], v[18:19] op_sel_hi:[1,0]
	s_nop 1
	v_mov_b32_dpp v18, v0 row_half_mirror row_mask:0xf bank_mask:0xf
	v_pk_mul_f32 v[16:17], v[32:33], v[16:17]
	v_pk_mul_f32 v[14:15], v[30:31], v[14:15]
	v_cvt_pk_bf16_f32 v10, v10, v11
	v_cvt_pk_bf16_f32 v11, v12, v13
	s_waitcnt lgkmcnt(0)
	v_add_f32_e32 v18, v0, v18
	v_lshlrev_b32_e32 v0, 11, v42
	v_cvt_pk_bf16_f32 v12, v14, v15
	v_cvt_pk_bf16_f32 v13, v16, v17
	v_lshl_add_u64 v[14:15], v[36:37], 0, v[0:1]
	s_nop 1
	v_mov_b32_dpp v19, v18 row_mirror row_mask:0xf bank_mask:0xf
	global_store_dwordx4 v[14:15], v[10:13], off
	v_lshl_add_u32 v14, v38, 8, v41
	ds_read_b128 v[14:17], v14
	v_lshl_add_u32 v10, v39, 8, v41
	ds_read_b128 v[10:13], v10
	s_waitcnt lgkmcnt(2)
	v_add_f32_e32 v0, v18, v19
	v_fmamk_f32 v0, v0, 0x3c000000, v227
	s_waitcnt vmcnt(6)
	v_lshlrev_b32_e32 v24, 16, v6
	v_and_b32_e32 v25, 0xffff0000, v6
	s_waitcnt lgkmcnt(0)
	v_lshlrev_b32_e32 v22, 16, v10
	v_and_b32_e32 v23, 0xffff0000, v10
	v_lshlrev_b32_e32 v10, 16, v11
	v_and_b32_e32 v11, 0xffff0000, v11
	v_lshlrev_b32_e32 v6, 16, v7
	v_and_b32_e32 v7, 0xffff0000, v7
	v_rsq_f32_e32 v0, v0
	v_pk_fma_f32 v[22:23], v[212:213], v[24:25], v[22:23] neg_lo:[1,0,0] neg_hi:[1,0,0]
	v_pk_fma_f32 v[10:11], v[26:27], v[6:7], v[10:11]
	v_lshlrev_b32_e32 v6, 16, v12
	v_and_b32_e32 v7, 0xffff0000, v12
	v_lshlrev_b32_e32 v12, 16, v13
	v_and_b32_e32 v13, 0xffff0000, v13
	v_lshlrev_b32_e32 v24, 16, v8
	v_and_b32_e32 v25, 0xffff0000, v8
	v_lshlrev_b32_e32 v8, 16, v9
	v_and_b32_e32 v9, 0xffff0000, v9
	v_pk_fma_f32 v[24:25], v[212:213], v[24:25], v[6:7] neg_lo:[1,0,0] neg_hi:[1,0,0]
	v_pk_fma_f32 v[12:13], v[26:27], v[8:9], v[12:13]
	v_pk_mul_f32 v[6:7], v[10:11], v[10:11]
	v_pk_mul_f32 v[8:9], v[22:23], v[22:23]
	v_pk_mul_f32 v[18:19], v[20:21], v[0:1] op_sel_hi:[1,0]
	v_pk_mov_b32 v[42:43], v[8:9], v[6:7] op_sel:[1,0]
	v_mov_b32_e32 v9, v7
	v_pk_add_f32 v[6:7], v[42:43], v[8:9]
	v_pk_mul_f32 v[8:9], v[12:13], v[12:13]
	v_pk_mul_f32 v[42:43], v[24:25], v[24:25]
	v_pk_mul_f32 v[20:21], v[50:51], v[0:1] op_sel_hi:[1,0]
	v_mov_b32_e32 v50, v8
	v_mov_b32_e32 v51, v42
	v_mov_b32_e32 v42, v9
	v_pk_add_f32 v[8:9], v[50:51], v[42:43]
	v_add_f32_e32 v6, v6, v7
	v_add_f32_e32 v6, v9, v6
	v_add_f32_e32 v41, v8, v6
	s_nop 1
	v_mov_b32_dpp v42, v41 quad_perm:[1,0,3,2] row_mask:0xf bank_mask:0xf
	v_pk_mul_f32 v[8:9], v[34:35], v[20:21]
	v_pk_mul_f32 v[6:7], v[28:29], v[18:19]
	v_pk_mul_f32 v[18:19], v[54:55], v[0:1] op_sel_hi:[1,0]
	v_pk_mul_f32 v[20:21], v[52:53], v[0:1] op_sel_hi:[1,0]
	s_waitcnt lgkmcnt(0)
	v_add_f32_e32 v0, v41, v42
	s_nop 1
	v_mov_b32_dpp v41, v0 quad_perm:[2,3,0,1] row_mask:0xf bank_mask:0xf
	v_pk_mul_f32 v[20:21], v[32:33], v[20:21]
	v_pk_mul_f32 v[18:19], v[30:31], v[18:19]
	v_cvt_pk_bf16_f32 v6, v6, v7
	v_cvt_pk_bf16_f32 v7, v8, v9
	s_waitcnt lgkmcnt(0)
	v_add_f32_e32 v41, v0, v41
	s_nop 1
	v_mov_b32_dpp v42, v41 row_half_mirror row_mask:0xf bank_mask:0xf
	v_lshlrev_b32_e32 v0, 11, v40
	v_cvt_pk_bf16_f32 v8, v18, v19
	v_cvt_pk_bf16_f32 v9, v20, v21
	v_lshl_add_u64 v[18:19], v[36:37], 0, v[0:1]
	s_waitcnt lgkmcnt(0)
	v_add_f32_e32 v0, v41, v42
	v_lshlrev_b32_e32 v20, 16, v14
	v_and_b32_e32 v21, 0xffff0000, v14
	v_lshlrev_b32_e32 v14, 16, v15
	v_and_b32_e32 v15, 0xffff0000, v15
	s_waitcnt vmcnt(5)
	v_lshlrev_b32_e32 v40, 16, v2
	v_and_b32_e32 v41, 0xffff0000, v2
	v_lshlrev_b32_e32 v2, 16, v3
	v_and_b32_e32 v3, 0xffff0000, v3
	v_pk_fma_f32 v[20:21], v[212:213], v[40:41], v[20:21] neg_lo:[1,0,0] neg_hi:[1,0,0]
	v_pk_fma_f32 v[14:15], v[26:27], v[2:3], v[14:15]
	v_lshlrev_b32_e32 v2, 16, v16
	v_and_b32_e32 v3, 0xffff0000, v16
	v_lshlrev_b32_e32 v16, 16, v17
	v_and_b32_e32 v17, 0xffff0000, v17
	v_lshlrev_b32_e32 v40, 16, v4
	v_and_b32_e32 v41, 0xffff0000, v4
	v_lshlrev_b32_e32 v4, 16, v5
	v_and_b32_e32 v5, 0xffff0000, v5
	v_pk_fma_f32 v[40:41], v[212:213], v[40:41], v[2:3] neg_lo:[1,0,0] neg_hi:[1,0,0]
	v_pk_fma_f32 v[16:17], v[26:27], v[4:5], v[16:17]
	v_pk_mul_f32 v[2:3], v[14:15], v[14:15]
	v_pk_mul_f32 v[4:5], v[20:21], v[20:21]
	s_nop 1
	v_mov_b32_dpp v44, v0 row_mirror row_mask:0xf bank_mask:0xf
	v_pk_mov_b32 v[26:27], v[4:5], v[2:3] op_sel:[1,0]
	v_mov_b32_e32 v5, v3
	v_pk_add_f32 v[2:3], v[26:27], v[4:5]
	v_pk_mul_f32 v[4:5], v[16:17], v[16:17]
	v_pk_mul_f32 v[26:27], v[40:41], v[40:41]
	v_mov_b32_e32 v42, v4
	v_mov_b32_e32 v43, v26
	v_mov_b32_e32 v26, v5
	v_pk_add_f32 v[4:5], v[42:43], v[26:27]
	v_add_f32_e32 v2, v2, v3
	v_add_f32_e32 v2, v5, v2
	v_add_f32_e32 v2, v4, v2
	s_nop 1
	v_mov_b32_dpp v3, v2 quad_perm:[1,0,3,2] row_mask:0xf bank_mask:0xf
	s_waitcnt lgkmcnt(0)
	v_add_f32_e32 v0, v0, v44
	global_store_dwordx4 v[18:19], v[6:9], off
	v_fmamk_f32 v0, v0, 0x3c000000, v227
	v_rsq_f32_e32 v0, v0
	s_waitcnt lgkmcnt(0)
	v_add_f32_e32 v6, v2, v3
	s_nop 1
	v_mov_b32_dpp v7, v6 quad_perm:[2,3,0,1] row_mask:0xf bank_mask:0xf
	v_pk_mul_f32 v[4:5], v[10:11], v[0:1] op_sel_hi:[1,0]
	v_pk_mul_f32 v[2:3], v[22:23], v[0:1] op_sel_hi:[1,0]
	v_pk_mul_f32 v[8:9], v[12:13], v[0:1] op_sel_hi:[1,0]
	s_waitcnt lgkmcnt(0)
	v_add_f32_e32 v10, v6, v7
	s_nop 1
	v_mov_b32_dpp v11, v10 row_half_mirror row_mask:0xf bank_mask:0xf
	v_pk_mul_f32 v[6:7], v[24:25], v[0:1] op_sel_hi:[1,0]
	v_pk_mul_f32 v[4:5], v[34:35], v[4:5]
	v_pk_mul_f32 v[2:3], v[28:29], v[2:3]
	v_pk_mul_f32 v[6:7], v[30:31], v[6:7]
	s_waitcnt lgkmcnt(0)
	v_add_f32_e32 v0, v10, v11
	s_nop 1
	v_mov_b32_dpp v10, v0 row_mirror row_mask:0xf bank_mask:0xf
	v_cvt_pk_bf16_f32 v2, v2, v3
	v_cvt_pk_bf16_f32 v3, v4, v5
	v_cvt_pk_bf16_f32 v4, v6, v7
	v_pk_mul_f32 v[8:9], v[32:33], v[8:9]
	s_waitcnt lgkmcnt(0)
	v_add_f32_e32 v0, v0, v10
	v_fmamk_f32 v0, v0, 0x3c000000, v227
	v_rsq_f32_e32 v6, v0
	v_lshlrev_b32_e32 v0, 11, v39
	v_cvt_pk_bf16_f32 v5, v8, v9
	v_lshl_add_u64 v[8:9], v[36:37], 0, v[0:1]
	global_store_dwordx4 v[8:9], v[2:5], off
	v_pk_mul_f32 v[8:9], v[40:41], v[6:7] op_sel_hi:[1,0]
	v_lshlrev_b32_e32 v0, 11, v38
	v_pk_mul_f32 v[2:3], v[20:21], v[6:7] op_sel_hi:[1,0]
	v_pk_mul_f32 v[4:5], v[14:15], v[6:7] op_sel_hi:[1,0]
	v_pk_mul_f32 v[6:7], v[16:17], v[6:7] op_sel_hi:[1,0]
	v_pk_mul_f32 v[4:5], v[34:35], v[4:5]
	v_pk_mul_f32 v[2:3], v[28:29], v[2:3]
	v_pk_mul_f32 v[6:7], v[32:33], v[6:7]
	v_pk_mul_f32 v[8:9], v[30:31], v[8:9]
	v_cvt_pk_bf16_f32 v2, v2, v3
	v_cvt_pk_bf16_f32 v3, v4, v5
	v_cvt_pk_bf16_f32 v4, v8, v9
	v_cvt_pk_bf16_f32 v5, v6, v7
	v_lshl_add_u64 v[6:7], v[36:37], 0, v[0:1]
	global_store_dwordx4 v[6:7], v[2:5], off
	s_waitcnt lgkmcnt(0)
	s_barrier

.LBB0_1344:
	s_or_b64 exec, exec, s[10:11]
	v_mov_b32_e32 v215, v1
	v_lshl_add_u64 v[2:3], s[58:59], 0, v[214:215]
	v_lshlrev_b32_e32 v0, 10, v99
	s_waitcnt lgkmcnt(0)
	s_barrier
	v_lshl_add_u64 v[6:7], v[2:3], 0, v[0:1]
	global_load_dwordx4 v[2:5], v[6:7], off
	v_lshlrev_b32_e32 v0, 5, v231
	v_lshlrev_b32_e32 v8, 2, v230
	v_lshl_add_u32 v9, v99, 8, v41
	v_lshl_add_u32 v12, v49, 8, v41
	global_load_dwordx4 v[30:33], v0, s[16:17] offset:528
	global_load_dwordx4 v[34:37], v0, s[16:17] offset:512
	v_xor_b32_e32 v48, 4, v8
	v_xor_b32_e32 v47, 8, v8
	v_xor_b32_e32 v46, 16, v8
	v_xor_b32_e32 v45, 32, v8
	ds_read_b128 v[8:11], v9
	ds_read_b128 v[50:53], v12
	v_add_co_u32_e32 v12, vcc, 0x1000, v6
	v_xor_b32_e32 v26, 0x80000000, v212
	s_nop 0
	v_addc_co_u32_e32 v13, vcc, 0, v7, vcc
	global_load_dwordx4 v[54:57], v[12:13], off
	v_add_co_u32_e32 v14, vcc, 0x2000, v6
	v_mov_b32_e32 v27, v26
	s_nop 0
	v_addc_co_u32_e32 v15, vcc, 0, v7, vcc
	v_add_co_u32_e32 v12, vcc, 0x3000, v6
	s_waitcnt lgkmcnt(1)
	v_lshlrev_b32_e32 v28, 16, v8
	v_addc_co_u32_e32 v13, vcc, 0, v7, vcc
	global_load_dwordx4 v[22:25], v[14:15], off
	global_load_dwordx4 v[18:21], v[12:13], off
	v_and_b32_e32 v29, 0xffff0000, v8
	v_lshlrev_b32_e32 v8, 16, v9
	v_and_b32_e32 v9, 0xffff0000, v9
	v_lshlrev_b32_e32 v58, 16, v10
	v_and_b32_e32 v59, 0xffff0000, v10
	v_lshlrev_b32_e32 v10, 16, v11
	v_and_b32_e32 v11, 0xffff0000, v11
	s_waitcnt lgkmcnt(0)
	v_lshlrev_b32_e32 v60, 16, v50
	v_and_b32_e32 v61, 0xffff0000, v50
	v_lshlrev_b32_e32 v50, 16, v51
	v_and_b32_e32 v51, 0xffff0000, v51
	v_add_co_u32_e32 v16, vcc, 0x4000, v6
	s_lshl_b64 s[10:11], s[52:53], 11
	s_nop 0
	v_addc_co_u32_e32 v17, vcc, 0, v7, vcc
	v_add_co_u32_e32 v12, vcc, 0x5000, v6
	s_movk_i32 s12, 0x6000
	s_nop 0
	v_addc_co_u32_e32 v13, vcc, 0, v7, vcc
	s_add_u32 s10, s83, s10
	s_addc_u32 s11, s84, s11
	s_waitcnt vmcnt(5)
	v_lshlrev_b32_e32 v14, 16, v2
	v_and_b32_e32 v15, 0xffff0000, v2
	v_lshlrev_b32_e32 v2, 16, v3
	v_and_b32_e32 v3, 0xffff0000, v3
	v_lshlrev_b32_e32 v62, 16, v4
	v_and_b32_e32 v63, 0xffff0000, v4
	v_lshlrev_b32_e32 v4, 16, v5
	v_and_b32_e32 v5, 0xffff0000, v5
	v_pk_fma_f32 v[64:65], v[212:213], v[14:15], v[28:29] neg_lo:[1,0,0] neg_hi:[1,0,0]
	v_pk_fma_f32 v[66:67], v[26:27], v[2:3], v[8:9]
	v_pk_fma_f32 v[58:59], v[212:213], v[62:63], v[58:59] neg_lo:[1,0,0] neg_hi:[1,0,0]
	v_pk_fma_f32 v[62:63], v[26:27], v[4:5], v[10:11]
	v_pk_mul_f32 v[2:3], v[66:67], v[66:67]
	v_pk_mul_f32 v[4:5], v[64:65], v[64:65]
	v_pk_mul_f32 v[8:9], v[62:63], v[62:63]
	v_pk_mul_f32 v[10:11], v[58:59], v[58:59]
	v_pk_mov_b32 v[14:15], v[4:5], v[2:3] op_sel:[1,0]
	v_mov_b32_e32 v5, v3
	v_mov_b32_e32 v2, v8
	v_mov_b32_e32 v3, v10
	v_mov_b32_e32 v10, v9
	v_pk_add_f32 v[4:5], v[14:15], v[4:5]
	v_pk_add_f32 v[2:3], v[2:3], v[10:11]
	v_add_f32_e32 v0, v4, v5
	v_add_f32_e32 v0, v3, v0
	v_add_f32_e32 v0, v2, v0
	s_nop 1
	v_mov_b32_dpp v3, v0 quad_perm:[1,0,3,2] row_mask:0xf bank_mask:0xf
	s_waitcnt vmcnt(3)
	v_pk_mul_f32 v[28:29], v[34:35], s[50:51] op_sel_hi:[1,0]
	v_pk_mul_f32 v[34:35], v[36:37], s[50:51] op_sel_hi:[1,0]
	s_waitcnt vmcnt(2)
	v_lshlrev_b32_e32 v36, 16, v54
	v_and_b32_e32 v37, 0xffff0000, v54
	s_waitcnt lgkmcnt(0)
	v_add_f32_e32 v0, v0, v3
	s_nop 1
	v_mov_b32_dpp v5, v0 quad_perm:[2,3,0,1] row_mask:0xf bank_mask:0xf
	v_lshlrev_b32_e32 v54, 16, v55
	v_and_b32_e32 v55, 0xffff0000, v55
	v_pk_fma_f32 v[60:61], v[212:213], v[36:37], v[60:61] neg_lo:[1,0,0] neg_hi:[1,0,0]
	v_pk_fma_f32 v[54:55], v[26:27], v[54:55], v[50:51]
	s_waitcnt lgkmcnt(0)
	v_add_f32_e32 v0, v0, v5
	s_nop 1
	v_mov_b32_dpp v68, v0 row_half_mirror row_mask:0xf bank_mask:0xf
	v_lshlrev_b32_e32 v36, 16, v52
	v_and_b32_e32 v37, 0xffff0000, v52
	v_lshlrev_b32_e32 v50, 16, v53
	v_and_b32_e32 v51, 0xffff0000, v53
	s_waitcnt lgkmcnt(0)
	v_add_f32_e32 v0, v0, v68
	s_nop 1
	v_mov_b32_dpp v68, v0 row_mirror row_mask:0xf bank_mask:0xf
	v_lshlrev_b32_e32 v52, 16, v56
	v_and_b32_e32 v53, 0xffff0000, v56
	v_lshlrev_b32_e32 v56, 16, v57
	v_and_b32_e32 v57, 0xffff0000, v57
	s_waitcnt lgkmcnt(0)
	v_add_f32_e32 v0, v0, v68
	v_pk_fma_f32 v[68:69], v[212:213], v[52:53], v[36:37] neg_lo:[1,0,0] neg_hi:[1,0,0]
	v_pk_fma_f32 v[70:71], v[26:27], v[56:57], v[50:51]
	v_pk_mul_f32 v[36:37], v[54:55], v[54:55]
	v_pk_mul_f32 v[50:51], v[60:61], v[60:61]
	v_fmamk_f32 v0, v0, 0x3c000000, v227
	v_pk_mov_b32 v[52:53], v[50:51], v[36:37] op_sel:[1,0]
	v_mov_b32_e32 v51, v37
	v_pk_add_f32 v[36:37], v[52:53], v[50:51]
	v_pk_mul_f32 v[50:51], v[70:71], v[70:71]
	v_pk_mul_f32 v[52:53], v[68:69], v[68:69]
	v_mov_b32_e32 v56, v50
	v_mov_b32_e32 v57, v52
	v_mov_b32_e32 v52, v51
	v_pk_add_f32 v[50:51], v[56:57], v[52:53]
	v_add_f32_e32 v36, v36, v37
	v_add_f32_e32 v36, v51, v36
	v_add_f32_e32 v56, v50, v36
	s_nop 1
	v_mov_b32_dpp v57, v56 quad_perm:[1,0,3,2] row_mask:0xf bank_mask:0xf
	v_rsq_f32_e32 v0, v0
	global_load_dwordx4 v[14:17], v[16:17], off
	s_nop 0
	global_load_dwordx4 v[10:13], v[12:13], off
	v_add_co_u32_e32 v2, vcc, s12, v6
	v_pk_mul_f32 v[50:51], v[64:65], v[0:1] op_sel_hi:[1,0]
	s_waitcnt lgkmcnt(0)
	v_add_f32_e32 v64, v56, v57
	s_nop 1
	v_mov_b32_dpp v65, v64 quad_perm:[2,3,0,1] row_mask:0xf bank_mask:0xf
	v_pk_mul_f32 v[52:53], v[66:67], v[0:1] op_sel_hi:[1,0]
	v_pk_mul_f32 v[56:57], v[58:59], v[0:1] op_sel_hi:[1,0]
	v_pk_mul_f32 v[58:59], v[62:63], v[0:1] op_sel_hi:[1,0]
	v_addc_co_u32_e32 v3, vcc, 0, v7, vcc
	s_waitcnt lgkmcnt(0)
	v_add_f32_e32 v0, v64, v65
	s_nop 1
	v_mov_b32_dpp v62, v0 row_half_mirror row_mask:0xf bank_mask:0xf
	v_pk_mul_f32 v[30:31], v[30:31], s[50:51] op_sel_hi:[1,0]
	v_pk_mul_f32 v[32:33], v[32:33], s[50:51] op_sel_hi:[1,0]
	v_add_co_u32_e32 v4, vcc, 0x7000, v6
	s_waitcnt lgkmcnt(0)
	v_add_f32_e32 v62, v0, v62
	s_nop 1
	v_mov_b32_dpp v63, v62 row_mirror row_mask:0xf bank_mask:0xf
	v_lshl_add_u64 v[36:37], s[10:11], 0, v[214:215]
	v_pk_mul_f32 v[52:53], v[34:35], v[52:53]
	v_pk_mul_f32 v[50:51], v[28:29], v[50:51]
	v_pk_mul_f32 v[58:59], v[32:33], v[58:59]
	v_pk_mul_f32 v[56:57], v[30:31], v[56:57]
	v_lshlrev_b32_e32 v0, 11, v99
	v_addc_co_u32_e32 v5, vcc, 0, v7, vcc
	v_cvt_pk_bf16_f32 v50, v50, v51
	v_cvt_pk_bf16_f32 v51, v52, v53
	v_cvt_pk_bf16_f32 v52, v56, v57
	v_cvt_pk_bf16_f32 v53, v58, v59
	v_lshl_add_u64 v[56:57], v[36:37], 0, v[0:1]
	s_waitcnt lgkmcnt(0)
	v_add_f32_e32 v0, v62, v63
	global_load_dwordx4 v[6:9], v[2:3], off
	s_nop 0
	global_load_dwordx4 v[2:5], v[4:5], off
	v_fmamk_f32 v0, v0, 0x3c000000, v227
	global_store_dwordx4 v[56:57], v[50:53], off
	v_rsq_f32_e32 v0, v0
	s_waitcnt vmcnt(6)
	v_lshlrev_b32_e32 v64, 16, v22
	v_lshl_add_u32 v50, v44, 8, v41
	ds_read_b128 v[50:53], v50
	v_pk_mul_f32 v[58:59], v[60:61], v[0:1] op_sel_hi:[1,0]
	v_pk_mul_f32 v[60:61], v[54:55], v[0:1] op_sel_hi:[1,0]
	v_lshl_add_u32 v54, v43, 8, v41
	ds_read_b128 v[54:57], v54
	s_waitcnt lgkmcnt(1)
	v_lshlrev_b32_e32 v62, 16, v50
	v_and_b32_e32 v63, 0xffff0000, v50
	v_lshlrev_b32_e32 v50, 16, v51
	v_and_b32_e32 v51, 0xffff0000, v51
	v_and_b32_e32 v65, 0xffff0000, v22
	v_lshlrev_b32_e32 v22, 16, v23
	v_and_b32_e32 v23, 0xffff0000, v23
	v_pk_fma_f32 v[62:63], v[212:213], v[64:65], v[62:63] neg_lo:[1,0,0] neg_hi:[1,0,0]
	v_pk_fma_f32 v[50:51], v[26:27], v[22:23], v[50:51]
	v_lshlrev_b32_e32 v22, 16, v52
	v_and_b32_e32 v23, 0xffff0000, v52
	v_lshlrev_b32_e32 v52, 16, v53
	v_and_b32_e32 v53, 0xffff0000, v53
	v_lshlrev_b32_e32 v64, 16, v24
	v_and_b32_e32 v65, 0xffff0000, v24
	v_lshlrev_b32_e32 v24, 16, v25
	v_and_b32_e32 v25, 0xffff0000, v25
	v_pk_fma_f32 v[64:65], v[212:213], v[64:65], v[22:23] neg_lo:[1,0,0] neg_hi:[1,0,0]
	v_pk_fma_f32 v[52:53], v[26:27], v[24:25], v[52:53]
	v_pk_mul_f32 v[22:23], v[50:51], v[50:51]
	v_pk_mul_f32 v[24:25], v[62:63], v[62:63]
	s_nop 0
	v_pk_mov_b32 v[66:67], v[24:25], v[22:23] op_sel:[1,0]
	v_mov_b32_e32 v25, v23
	v_pk_add_f32 v[22:23], v[66:67], v[24:25]
	v_pk_mul_f32 v[24:25], v[52:53], v[52:53]
	v_pk_mul_f32 v[66:67], v[64:65], v[64:65]
	v_mov_b32_e32 v72, v24
	v_mov_b32_e32 v73, v66
	v_mov_b32_e32 v66, v25
	v_pk_add_f32 v[24:25], v[72:73], v[66:67]
	v_add_f32_e32 v22, v22, v23
	v_add_f32_e32 v22, v25, v22
	v_add_f32_e32 v66, v24, v22
	s_nop 1
	v_mov_b32_dpp v67, v66 quad_perm:[1,0,3,2] row_mask:0xf bank_mask:0xf
	v_pk_mul_f32 v[24:25], v[34:35], v[60:61]
	v_pk_mul_f32 v[22:23], v[28:29], v[58:59]
	v_pk_mul_f32 v[58:59], v[68:69], v[0:1] op_sel_hi:[1,0]
	v_pk_mul_f32 v[60:61], v[70:71], v[0:1] op_sel_hi:[1,0]
	s_waitcnt lgkmcnt(0)
	v_add_f32_e32 v0, v66, v67
	s_nop 1
	v_mov_b32_dpp v66, v0 quad_perm:[2,3,0,1] row_mask:0xf bank_mask:0xf
	v_pk_mul_f32 v[60:61], v[32:33], v[60:61]
	v_pk_mul_f32 v[58:59], v[30:31], v[58:59]
	v_cvt_pk_bf16_f32 v22, v22, v23
	v_cvt_pk_bf16_f32 v23, v24, v25
	s_waitcnt lgkmcnt(0)
	v_add_f32_e32 v66, v0, v66
	s_nop 1
	v_mov_b32_dpp v67, v66 row_half_mirror row_mask:0xf bank_mask:0xf
	v_lshlrev_b32_e32 v0, 11, v49
	v_cvt_pk_bf16_f32 v24, v58, v59
	v_cvt_pk_bf16_f32 v25, v60, v61
	v_lshl_add_u64 v[58:59], v[36:37], 0, v[0:1]
	s_waitcnt lgkmcnt(0)
	v_add_f32_e32 v0, v66, v67
	v_lshlrev_b32_e32 v60, 16, v54
	v_and_b32_e32 v61, 0xffff0000, v54
	v_lshlrev_b32_e32 v54, 16, v55
	v_and_b32_e32 v55, 0xffff0000, v55
	s_waitcnt vmcnt(5)
	v_lshlrev_b32_e32 v66, 16, v18
	v_and_b32_e32 v67, 0xffff0000, v18
	v_lshlrev_b32_e32 v18, 16, v19
	v_and_b32_e32 v19, 0xffff0000, v19
	v_pk_fma_f32 v[60:61], v[212:213], v[66:67], v[60:61] neg_lo:[1,0,0] neg_hi:[1,0,0]
	v_pk_fma_f32 v[54:55], v[26:27], v[18:19], v[54:55]
	v_lshlrev_b32_e32 v18, 16, v56
	v_and_b32_e32 v19, 0xffff0000, v56
	v_lshlrev_b32_e32 v56, 16, v57
	v_and_b32_e32 v57, 0xffff0000, v57
	v_lshlrev_b32_e32 v66, 16, v20
	v_and_b32_e32 v67, 0xffff0000, v20
	v_lshlrev_b32_e32 v20, 16, v21
	v_and_b32_e32 v21, 0xffff0000, v21
	v_pk_fma_f32 v[66:67], v[212:213], v[66:67], v[18:19] neg_lo:[1,0,0] neg_hi:[1,0,0]
	v_pk_fma_f32 v[56:57], v[26:27], v[20:21], v[56:57]
	v_pk_mul_f32 v[18:19], v[54:55], v[54:55]
	v_pk_mul_f32 v[20:21], v[60:61], v[60:61]
	s_nop 1
	v_mov_b32_dpp v49, v0 row_mirror row_mask:0xf bank_mask:0xf
	v_pk_mov_b32 v[68:69], v[20:21], v[18:19] op_sel:[1,0]
	v_mov_b32_e32 v21, v19
	v_pk_add_f32 v[18:19], v[68:69], v[20:21]
	v_pk_mul_f32 v[20:21], v[56:57], v[56:57]
	v_pk_mul_f32 v[68:69], v[66:67], v[66:67]
	v_mov_b32_e32 v70, v20
	v_mov_b32_e32 v71, v68
	v_mov_b32_e32 v68, v21
	v_pk_add_f32 v[20:21], v[70:71], v[68:69]
	v_add_f32_e32 v18, v18, v19
	v_add_f32_e32 v18, v21, v18
	v_add_f32_e32 v18, v20, v18
	s_nop 1
	v_mov_b32_dpp v19, v18 quad_perm:[1,0,3,2] row_mask:0xf bank_mask:0xf
	global_store_dwordx4 v[58:59], v[22:25], off
	s_waitcnt lgkmcnt(0)
	v_add_f32_e32 v0, v0, v49
	v_fmamk_f32 v0, v0, 0x3c000000, v227
	v_rsq_f32_e32 v0, v0
	s_waitcnt lgkmcnt(0)
	v_add_f32_e32 v22, v18, v19
	s_nop 1
	v_mov_b32_dpp v23, v22 quad_perm:[2,3,0,1] row_mask:0xf bank_mask:0xf
	v_pk_mul_f32 v[20:21], v[50:51], v[0:1] op_sel_hi:[1,0]
	v_pk_mul_f32 v[18:19], v[62:63], v[0:1] op_sel_hi:[1,0]
	v_pk_mul_f32 v[24:25], v[52:53], v[0:1] op_sel_hi:[1,0]
	s_waitcnt lgkmcnt(0)
	v_add_f32_e32 v49, v22, v23
	s_nop 1
	v_mov_b32_dpp v50, v49 row_half_mirror row_mask:0xf bank_mask:0xf
	v_pk_mul_f32 v[22:23], v[64:65], v[0:1] op_sel_hi:[1,0]
	v_pk_mul_f32 v[20:21], v[34:35], v[20:21]
	v_pk_mul_f32 v[18:19], v[28:29], v[18:19]
	v_pk_mul_f32 v[22:23], v[30:31], v[22:23]
	s_waitcnt lgkmcnt(0)
	v_add_f32_e32 v0, v49, v50
	s_nop 1
	v_mov_b32_dpp v49, v0 row_mirror row_mask:0xf bank_mask:0xf
	v_pk_mul_f32 v[24:25], v[32:33], v[24:25]
	v_cvt_pk_bf16_f32 v18, v18, v19
	v_cvt_pk_bf16_f32 v19, v20, v21
	v_cvt_pk_bf16_f32 v20, v22, v23
	v_lshl_add_u32 v22, v42, 8, v41
	v_cvt_pk_bf16_f32 v21, v24, v25
	ds_read_b128 v[22:25], v22
	s_waitcnt lgkmcnt(1)
	v_add_f32_e32 v0, v0, v49
	v_fmamk_f32 v0, v0, 0x3c000000, v227
	v_rsq_f32_e32 v58, v0
	v_lshl_add_u32 v0, v40, 8, v41
	ds_read_b128 v[50:53], v0
	s_waitcnt lgkmcnt(1)
	v_lshlrev_b32_e32 v62, 16, v22
	v_and_b32_e32 v63, 0xffff0000, v22
	v_lshlrev_b32_e32 v22, 16, v23
	v_and_b32_e32 v23, 0xffff0000, v23
	s_waitcnt vmcnt(5)
	v_lshlrev_b32_e32 v64, 16, v14
	v_and_b32_e32 v65, 0xffff0000, v14
	v_lshlrev_b32_e32 v14, 16, v15
	v_and_b32_e32 v15, 0xffff0000, v15
	v_pk_fma_f32 v[62:63], v[212:213], v[64:65], v[62:63] neg_lo:[1,0,0] neg_hi:[1,0,0]
	v_pk_fma_f32 v[22:23], v[26:27], v[14:15], v[22:23]
	v_lshlrev_b32_e32 v14, 16, v24
	v_and_b32_e32 v15, 0xffff0000, v24
	v_lshlrev_b32_e32 v24, 16, v25
	v_and_b32_e32 v25, 0xffff0000, v25
	v_lshlrev_b32_e32 v64, 16, v16
	v_and_b32_e32 v65, 0xffff0000, v16
	v_lshlrev_b32_e32 v16, 16, v17
	v_and_b32_e32 v17, 0xffff0000, v17
	v_pk_fma_f32 v[64:65], v[212:213], v[64:65], v[14:15] neg_lo:[1,0,0] neg_hi:[1,0,0]
	v_pk_fma_f32 v[24:25], v[26:27], v[16:17], v[24:25]
	v_pk_mul_f32 v[14:15], v[22:23], v[22:23]
	v_pk_mul_f32 v[16:17], v[62:63], v[62:63]
	s_nop 0
	v_pk_mov_b32 v[68:69], v[16:17], v[14:15] op_sel:[1,0]
	v_mov_b32_e32 v17, v15
	v_pk_add_f32 v[14:15], v[68:69], v[16:17]
	v_pk_mul_f32 v[16:17], v[24:25], v[24:25]
	v_pk_mul_f32 v[68:69], v[64:65], v[64:65]
	v_mov_b32_e32 v70, v16
	v_mov_b32_e32 v71, v68
	v_mov_b32_e32 v68, v17
	v_pk_add_f32 v[16:17], v[70:71], v[68:69]
	v_add_f32_e32 v0, v14, v15
	v_add_f32_e32 v0, v17, v0
	v_add_f32_e32 v16, v16, v0
	s_nop 1
	v_mov_b32_dpp v17, v16 quad_perm:[1,0,3,2] row_mask:0xf bank_mask:0xf
	v_lshlrev_b32_e32 v0, 11, v44
	v_lshl_add_u64 v[14:15], v[36:37], 0, v[0:1]
	global_store_dwordx4 v[14:15], v[18:21], off
	v_pk_mul_f32 v[14:15], v[60:61], v[58:59] op_sel_hi:[1,0]
	s_waitcnt lgkmcnt(0)
	v_add_f32_e32 v0, v16, v17
	s_nop 1
	v_mov_b32_dpp v20, v0 quad_perm:[2,3,0,1] row_mask:0xf bank_mask:0xf
	v_pk_mul_f32 v[16:17], v[54:55], v[58:59] op_sel_hi:[1,0]
	v_pk_mul_f32 v[14:15], v[28:29], v[14:15]
	v_pk_mul_f32 v[16:17], v[34:35], v[16:17]
	v_cvt_pk_bf16_f32 v14, v14, v15
	s_waitcnt lgkmcnt(0)
	v_add_f32_e32 v0, v0, v20
	s_nop 1
	v_mov_b32_dpp v44, v0 row_half_mirror row_mask:0xf bank_mask:0xf
	v_pk_mul_f32 v[20:21], v[56:57], v[58:59] op_sel_hi:[1,0]
	v_cvt_pk_bf16_f32 v15, v16, v17
	v_pk_mul_f32 v[20:21], v[32:33], v[20:21]
	s_waitcnt vmcnt(5)
	v_lshlrev_b32_e32 v54, 16, v10
	v_cvt_pk_bf16_f32 v17, v20, v21
	v_lshlrev_b32_e32 v20, 16, v50
	v_and_b32_e32 v21, 0xffff0000, v50
	v_lshlrev_b32_e32 v50, 16, v51
	v_and_b32_e32 v51, 0xffff0000, v51
	v_and_b32_e32 v55, 0xffff0000, v10
	v_lshlrev_b32_e32 v10, 16, v11
	v_and_b32_e32 v11, 0xffff0000, v11
	v_pk_fma_f32 v[20:21], v[212:213], v[54:55], v[20:21] neg_lo:[1,0,0] neg_hi:[1,0,0]
	v_pk_fma_f32 v[50:51], v[26:27], v[10:11], v[50:51]
	v_lshlrev_b32_e32 v10, 16, v52
	v_and_b32_e32 v11, 0xffff0000, v52
	v_lshlrev_b32_e32 v52, 16, v53
	v_and_b32_e32 v53, 0xffff0000, v53
	v_lshlrev_b32_e32 v54, 16, v12
	v_and_b32_e32 v55, 0xffff0000, v12
	v_lshlrev_b32_e32 v12, 16, v13
	v_and_b32_e32 v13, 0xffff0000, v13
	v_pk_fma_f32 v[54:55], v[212:213], v[54:55], v[10:11] neg_lo:[1,0,0] neg_hi:[1,0,0]
	v_pk_fma_f32 v[52:53], v[26:27], v[12:13], v[52:53]
	v_pk_mul_f32 v[10:11], v[50:51], v[50:51]
	v_pk_mul_f32 v[12:13], v[20:21], v[20:21]
	s_waitcnt lgkmcnt(0)
	v_add_f32_e32 v44, v0, v44
	v_pk_mov_b32 v[56:57], v[12:13], v[10:11] op_sel:[1,0]
	v_mov_b32_e32 v13, v11
	s_nop 1
	v_mov_b32_dpp v49, v44 row_mirror row_mask:0xf bank_mask:0xf
	v_pk_add_f32 v[10:11], v[56:57], v[12:13]
	v_pk_mul_f32 v[12:13], v[52:53], v[52:53]
	v_pk_mul_f32 v[56:57], v[54:55], v[54:55]
	v_pk_mul_f32 v[18:19], v[66:67], v[58:59] op_sel_hi:[1,0]
	v_mov_b32_e32 v58, v12
	v_mov_b32_e32 v59, v56
	v_mov_b32_e32 v56, v13
	v_pk_add_f32 v[12:13], v[58:59], v[56:57]
	v_add_f32_e32 v10, v10, v11
	v_pk_mul_f32 v[18:19], v[30:31], v[18:19]
	v_add_f32_e32 v10, v13, v10
	v_cvt_pk_bf16_f32 v16, v18, v19
	v_add_f32_e32 v19, v12, v10
	v_lshlrev_b32_e32 v0, 11, v43
	s_waitcnt lgkmcnt(0)
	v_add_f32_e32 v18, v44, v49
	s_nop 1
	v_mov_b32_dpp v43, v19 quad_perm:[1,0,3,2] row_mask:0xf bank_mask:0xf
	v_fmamk_f32 v18, v18, 0x3c000000, v227
	v_rsq_f32_e32 v18, v18
	v_lshl_add_u64 v[10:11], v[36:37], 0, v[0:1]
	global_store_dwordx4 v[10:11], v[14:17], off
	s_waitcnt lgkmcnt(0)
	v_add_f32_e32 v0, v19, v43
	v_pk_mul_f32 v[10:11], v[62:63], v[18:19] op_sel_hi:[1,0]
	v_pk_mul_f32 v[12:13], v[22:23], v[18:19] op_sel_hi:[1,0]
	s_nop 1
	v_mov_b32_dpp v19, v0 quad_perm:[2,3,0,1] row_mask:0xf bank_mask:0xf
	v_pk_mul_f32 v[12:13], v[34:35], v[12:13]
	v_pk_mul_f32 v[10:11], v[28:29], v[10:11]
	s_waitcnt lgkmcnt(0)
	v_add_f32_e32 v0, v0, v19
	v_pk_mul_f32 v[14:15], v[64:65], v[18:19] op_sel_hi:[1,0]
	v_pk_mul_f32 v[16:17], v[24:25], v[18:19] op_sel_hi:[1,0]
	s_nop 1
	v_mov_b32_dpp v18, v0 row_half_mirror row_mask:0xf bank_mask:0xf
	v_pk_mul_f32 v[16:17], v[32:33], v[16:17]
	v_pk_mul_f32 v[14:15], v[30:31], v[14:15]
	v_cvt_pk_bf16_f32 v10, v10, v11
	v_cvt_pk_bf16_f32 v11, v12, v13
	s_waitcnt lgkmcnt(0)
	v_add_f32_e32 v18, v0, v18
	v_lshlrev_b32_e32 v0, 11, v42
	v_cvt_pk_bf16_f32 v12, v14, v15
	v_cvt_pk_bf16_f32 v13, v16, v17
	v_lshl_add_u64 v[14:15], v[36:37], 0, v[0:1]
	s_nop 1
	v_mov_b32_dpp v19, v18 row_mirror row_mask:0xf bank_mask:0xf
	global_store_dwordx4 v[14:15], v[10:13], off
	v_lshl_add_u32 v14, v38, 8, v41
	ds_read_b128 v[14:17], v14
	v_lshl_add_u32 v10, v39, 8, v41
	ds_read_b128 v[10:13], v10
	s_waitcnt lgkmcnt(2)
	v_add_f32_e32 v0, v18, v19
	v_fmamk_f32 v0, v0, 0x3c000000, v227
	s_waitcnt vmcnt(6)
	v_lshlrev_b32_e32 v24, 16, v6
	v_and_b32_e32 v25, 0xffff0000, v6
	s_waitcnt lgkmcnt(0)
	v_lshlrev_b32_e32 v22, 16, v10
	v_and_b32_e32 v23, 0xffff0000, v10
	v_lshlrev_b32_e32 v10, 16, v11
	v_and_b32_e32 v11, 0xffff0000, v11
	v_lshlrev_b32_e32 v6, 16, v7
	v_and_b32_e32 v7, 0xffff0000, v7
	v_rsq_f32_e32 v0, v0
	v_pk_fma_f32 v[22:23], v[212:213], v[24:25], v[22:23] neg_lo:[1,0,0] neg_hi:[1,0,0]
	v_pk_fma_f32 v[10:11], v[26:27], v[6:7], v[10:11]
	v_lshlrev_b32_e32 v6, 16, v12
	v_and_b32_e32 v7, 0xffff0000, v12
	v_lshlrev_b32_e32 v12, 16, v13
	v_and_b32_e32 v13, 0xffff0000, v13
	v_lshlrev_b32_e32 v24, 16, v8
	v_and_b32_e32 v25, 0xffff0000, v8
	v_lshlrev_b32_e32 v8, 16, v9
	v_and_b32_e32 v9, 0xffff0000, v9
	v_pk_fma_f32 v[24:25], v[212:213], v[24:25], v[6:7] neg_lo:[1,0,0] neg_hi:[1,0,0]
	v_pk_fma_f32 v[12:13], v[26:27], v[8:9], v[12:13]
	v_pk_mul_f32 v[6:7], v[10:11], v[10:11]
	v_pk_mul_f32 v[8:9], v[22:23], v[22:23]
	v_pk_mul_f32 v[18:19], v[20:21], v[0:1] op_sel_hi:[1,0]
	v_pk_mov_b32 v[42:43], v[8:9], v[6:7] op_sel:[1,0]
	v_mov_b32_e32 v9, v7
	v_pk_add_f32 v[6:7], v[42:43], v[8:9]
	v_pk_mul_f32 v[8:9], v[12:13], v[12:13]
	v_pk_mul_f32 v[42:43], v[24:25], v[24:25]
	v_pk_mul_f32 v[20:21], v[50:51], v[0:1] op_sel_hi:[1,0]
	v_mov_b32_e32 v50, v8
	v_mov_b32_e32 v51, v42
	v_mov_b32_e32 v42, v9
	v_pk_add_f32 v[8:9], v[50:51], v[42:43]
	v_add_f32_e32 v6, v6, v7
	v_add_f32_e32 v6, v9, v6
	v_add_f32_e32 v41, v8, v6
	s_nop 1
	v_mov_b32_dpp v42, v41 quad_perm:[1,0,3,2] row_mask:0xf bank_mask:0xf
	v_pk_mul_f32 v[8:9], v[34:35], v[20:21]
	v_pk_mul_f32 v[6:7], v[28:29], v[18:19]
	v_pk_mul_f32 v[18:19], v[54:55], v[0:1] op_sel_hi:[1,0]
	v_pk_mul_f32 v[20:21], v[52:53], v[0:1] op_sel_hi:[1,0]
	s_waitcnt lgkmcnt(0)
	v_add_f32_e32 v0, v41, v42
	s_nop 1
	v_mov_b32_dpp v41, v0 quad_perm:[2,3,0,1] row_mask:0xf bank_mask:0xf
	v_pk_mul_f32 v[20:21], v[32:33], v[20:21]
	v_pk_mul_f32 v[18:19], v[30:31], v[18:19]
	v_cvt_pk_bf16_f32 v6, v6, v7
	v_cvt_pk_bf16_f32 v7, v8, v9
	s_waitcnt lgkmcnt(0)
	v_add_f32_e32 v41, v0, v41
	s_nop 1
	v_mov_b32_dpp v42, v41 row_half_mirror row_mask:0xf bank_mask:0xf
	v_lshlrev_b32_e32 v0, 11, v40
	v_cvt_pk_bf16_f32 v8, v18, v19
	v_cvt_pk_bf16_f32 v9, v20, v21
	v_lshl_add_u64 v[18:19], v[36:37], 0, v[0:1]
	s_waitcnt lgkmcnt(0)
	v_add_f32_e32 v0, v41, v42
	v_lshlrev_b32_e32 v20, 16, v14
	v_and_b32_e32 v21, 0xffff0000, v14
	v_lshlrev_b32_e32 v14, 16, v15
	v_and_b32_e32 v15, 0xffff0000, v15
	s_waitcnt vmcnt(5)
	v_lshlrev_b32_e32 v40, 16, v2
	v_and_b32_e32 v41, 0xffff0000, v2
	v_lshlrev_b32_e32 v2, 16, v3
	v_and_b32_e32 v3, 0xffff0000, v3
	v_pk_fma_f32 v[20:21], v[212:213], v[40:41], v[20:21] neg_lo:[1,0,0] neg_hi:[1,0,0]
	v_pk_fma_f32 v[14:15], v[26:27], v[2:3], v[14:15]
	v_lshlrev_b32_e32 v2, 16, v16
	v_and_b32_e32 v3, 0xffff0000, v16
	v_lshlrev_b32_e32 v16, 16, v17
	v_and_b32_e32 v17, 0xffff0000, v17
	v_lshlrev_b32_e32 v40, 16, v4
	v_and_b32_e32 v41, 0xffff0000, v4
	v_lshlrev_b32_e32 v4, 16, v5
	v_and_b32_e32 v5, 0xffff0000, v5
	v_pk_fma_f32 v[40:41], v[212:213], v[40:41], v[2:3] neg_lo:[1,0,0] neg_hi:[1,0,0]
	v_pk_fma_f32 v[16:17], v[26:27], v[4:5], v[16:17]
	v_pk_mul_f32 v[2:3], v[14:15], v[14:15]
	v_pk_mul_f32 v[4:5], v[20:21], v[20:21]
	s_nop 1
	v_mov_b32_dpp v44, v0 row_mirror row_mask:0xf bank_mask:0xf
	v_pk_mov_b32 v[26:27], v[4:5], v[2:3] op_sel:[1,0]
	v_mov_b32_e32 v5, v3
	v_pk_add_f32 v[2:3], v[26:27], v[4:5]
	v_pk_mul_f32 v[4:5], v[16:17], v[16:17]
	v_pk_mul_f32 v[26:27], v[40:41], v[40:41]
	v_mov_b32_e32 v42, v4
	v_mov_b32_e32 v43, v26
	v_mov_b32_e32 v26, v5
	v_pk_add_f32 v[4:5], v[42:43], v[26:27]
	v_add_f32_e32 v2, v2, v3
	v_add_f32_e32 v2, v5, v2
	v_add_f32_e32 v2, v4, v2
	s_nop 1
	v_mov_b32_dpp v3, v2 quad_perm:[1,0,3,2] row_mask:0xf bank_mask:0xf
	s_waitcnt lgkmcnt(0)
	v_add_f32_e32 v0, v0, v44
	global_store_dwordx4 v[18:19], v[6:9], off
	v_fmamk_f32 v0, v0, 0x3c000000, v227
	v_rsq_f32_e32 v0, v0
	s_waitcnt lgkmcnt(0)
	v_add_f32_e32 v6, v2, v3
	s_nop 1
	v_mov_b32_dpp v7, v6 quad_perm:[2,3,0,1] row_mask:0xf bank_mask:0xf
	v_pk_mul_f32 v[4:5], v[10:11], v[0:1] op_sel_hi:[1,0]
	v_pk_mul_f32 v[2:3], v[22:23], v[0:1] op_sel_hi:[1,0]
	v_pk_mul_f32 v[8:9], v[12:13], v[0:1] op_sel_hi:[1,0]
	s_waitcnt lgkmcnt(0)
	v_add_f32_e32 v10, v6, v7
	s_nop 1
	v_mov_b32_dpp v11, v10 row_half_mirror row_mask:0xf bank_mask:0xf
	v_pk_mul_f32 v[6:7], v[24:25], v[0:1] op_sel_hi:[1,0]
	v_pk_mul_f32 v[4:5], v[34:35], v[4:5]
	v_pk_mul_f32 v[2:3], v[28:29], v[2:3]
	v_pk_mul_f32 v[6:7], v[30:31], v[6:7]
	s_waitcnt lgkmcnt(0)
	v_add_f32_e32 v0, v10, v11
	s_nop 1
	v_mov_b32_dpp v10, v0 row_mirror row_mask:0xf bank_mask:0xf
	v_cvt_pk_bf16_f32 v2, v2, v3
	v_cvt_pk_bf16_f32 v3, v4, v5
	v_cvt_pk_bf16_f32 v4, v6, v7
	v_pk_mul_f32 v[8:9], v[32:33], v[8:9]
	s_waitcnt lgkmcnt(0)
	v_add_f32_e32 v0, v0, v10
	v_fmamk_f32 v0, v0, 0x3c000000, v227
	v_rsq_f32_e32 v6, v0
	v_lshlrev_b32_e32 v0, 11, v39
	v_cvt_pk_bf16_f32 v5, v8, v9
	v_lshl_add_u64 v[8:9], v[36:37], 0, v[0:1]
	global_store_dwordx4 v[8:9], v[2:5], off
	v_pk_mul_f32 v[8:9], v[40:41], v[6:7] op_sel_hi:[1,0]
	v_lshlrev_b32_e32 v0, 11, v38
	v_pk_mul_f32 v[2:3], v[20:21], v[6:7] op_sel_hi:[1,0]
	v_pk_mul_f32 v[4:5], v[14:15], v[6:7] op_sel_hi:[1,0]
	v_pk_mul_f32 v[6:7], v[16:17], v[6:7] op_sel_hi:[1,0]
	v_pk_mul_f32 v[4:5], v[34:35], v[4:5]
	v_pk_mul_f32 v[2:3], v[28:29], v[2:3]
	v_pk_mul_f32 v[6:7], v[32:33], v[6:7]
	v_pk_mul_f32 v[8:9], v[30:31], v[8:9]
	v_cvt_pk_bf16_f32 v2, v2, v3
	v_cvt_pk_bf16_f32 v3, v4, v5
	v_cvt_pk_bf16_f32 v4, v8, v9
	v_cvt_pk_bf16_f32 v5, v6, v7
	v_lshl_add_u64 v[6:7], v[36:37], 0, v[0:1]
	global_store_dwordx4 v[6:7], v[2:5], off
	s_waitcnt lgkmcnt(0)
	s_barrier
